# mla_post row loop: norm-gain and kv-latent loads hoisted to the top of the row iteration with counted waits
# speedup vs baseline: 1.0151x; 1.0063x over previous
.LBB0_2254:
	v_lshl_add_u64 v[0:1], s[50:51], 0, v[22:23]
	v_add_co_u32_e32 v0, vcc, 0xe000000, v0
	s_add_i32 s12, s18, 0xffff8000
	s_nop 0
	v_addc_co_u32_e32 v1, vcc, 0, v1, vcc
	global_load_dwordx2 v[2:3], v[0:1], off
	global_load_dwordx2 v[34:35], v[0:1], off offset:512
	global_load_dwordx2 v[36:37], v[0:1], off offset:1024
	global_load_dwordx2 v[38:39], v[6:7], off
	v_lshl_add_u64 v[60:61], s[50:51], 0, v[20:21]
	global_load_dwordx2 v[52:53], v[6:7], off offset:512
	global_load_dwordx2 v[54:55], v[6:7], off offset:1024
	global_load_dwordx4 v[56:59], v[60:61], off
	global_load_dwordx4 v[64:67], v[8:9], off
	s_cmp_lt_i32 s18, 0x8000
	s_cselect_b64 s[26:27], -1, 0
	s_mov_b64 s[20:21], s[18:19]
	s_waitcnt vmcnt(4) lgkmcnt(0)
	v_pk_mul_f32 v[0:1], v[2:3], v[2:3]
	v_pk_mul_f32 v[40:41], v[34:35], v[34:35]
	v_pk_mul_f32 v[42:43], v[36:37], v[36:37]
	v_add_f32_e32 v40, v40, v41
	v_add_f32_e32 v0, v0, v1
	v_add_f32_e32 v1, v42, v43
	v_add_f32_e32 v0, v0, v40
	v_add_f32_e32 v0, v0, v1
	ds_bpermute_b32 v1, v26, v0
	s_waitcnt lgkmcnt(0)
	v_add_f32_e32 v0, v0, v1
	ds_bpermute_b32 v1, v27, v0
	s_waitcnt lgkmcnt(0)
	v_add_f32_e32 v0, v0, v1
	ds_bpermute_b32 v1, v28, v0
	s_waitcnt lgkmcnt(0)
	v_add_f32_e32 v0, v0, v1
	ds_bpermute_b32 v1, v29, v0
	s_waitcnt lgkmcnt(0)
	v_add_f32_e32 v0, v0, v1
	ds_bpermute_b32 v1, v30, v0
	s_waitcnt lgkmcnt(0)
	v_add_f32_e32 v0, v0, v1
	ds_bpermute_b32 v1, v31, v0
	s_waitcnt lgkmcnt(0)
	v_add_f32_e32 v0, v0, v1
	v_fmamk_f32 v0, v0, 0x3b2aaaab, v32
	v_mul_f32_e32 v1, 0x4f800000, v0
	v_cmp_gt_f32_e32 vcc, s28, v0
	s_nop 1
	v_cndmask_b32_e32 v40, v0, v1, vcc
	v_sqrt_f32_e32 v41, v40
	v_lshl_add_u64 v[0:1], s[50:51], 0, v[16:17]
	v_add_u32_e32 v42, -1, v41
	v_add_u32_e32 v43, 1, v41
	v_fma_f32 v44, -v42, v41, v40
	v_fma_f32 v45, -v43, v41, v40
	v_cmp_ge_f32_e64 s[8:9], 0, v44
	s_nop 1
	v_cndmask_b32_e64 v41, v41, v42, s[8:9]
	v_cmp_lt_f32_e64 s[8:9], 0, v45
	s_nop 1
	v_cndmask_b32_e64 v41, v41, v43, s[8:9]
	v_mul_f32_e32 v42, 0x37800000, v41
	v_cndmask_b32_e32 v41, v41, v42, vcc
	v_cmp_class_f32_e32 vcc, v40, v33
	s_nop 1
	v_cndmask_b32_e32 v40, v41, v40, vcc
	v_div_scale_f32 v41, s[8:9], v40, v40, 1.0
	v_rcp_f32_e32 v42, v41
	v_add_co_u32_e32 v0, vcc, s29, v0
	s_and_b64 s[8:9], s[26:27], exec
	s_nop 0
	v_addc_co_u32_e32 v1, vcc, 0, v1, vcc
	v_fma_f32 v44, -v41, v42, 1.0
	v_div_scale_f32 v43, vcc, 1.0, v40, 1.0
	v_fmac_f32_e32 v42, v44, v42
	v_mul_f32_e32 v44, v43, v42
	v_fma_f32 v45, -v41, v44, v43
	v_fmac_f32_e32 v44, v45, v42
	v_fma_f32 v41, -v41, v44, v43
	v_div_fmas_f32 v41, v41, v42, v44
	v_div_fixup_f32 v40, v41, v40, 1.0
	v_mul_f32_e32 v2, v2, v40
	v_mul_f32_e32 v3, v3, v40
	v_mul_f32_e32 v2, v38, v2
	v_mul_f32_e32 v3, v39, v3
	v_cvt_pk_bf16_f32 v2, v2, v3
	global_store_dword v[0:1], v2, off
	v_mul_f32_e32 v34, v34, v40
	v_mul_f32_e32 v35, v35, v40
	v_lshl_add_u64 v[38:39], s[50:51], 0, v[20:21]
	s_cselect_b32 s10, s30, 0xc200000
	s_cselect_b32 s23, s19, 0
	s_cselect_b32 s22, s18, s12
	s_waitcnt vmcnt(4) lgkmcnt(0)
	v_mov_b64_e32 v[2:3], v[52:53]
	v_mul_f32_e32 v2, v2, v34
	v_mul_f32_e32 v3, v3, v35
	v_cvt_pk_bf16_f32 v2, v2, v3
	global_store_dword v[0:1], v2, off offset:256
	v_mul_f32_e32 v34, v36, v40
	v_mul_f32_e32 v35, v37, v40
	s_waitcnt vmcnt(4) lgkmcnt(0)
	v_mov_b64_e32 v[2:3], v[54:55]
	v_mul_f32_e32 v2, v2, v34
	v_mul_f32_e32 v3, v3, v35
	v_cvt_pk_bf16_f32 v2, v2, v3
	global_store_dword v[0:1], v2, off offset:512
	s_load_dwordx2 s[24:25], s[0:1], 0xd8
	s_waitcnt lgkmcnt(0)
	s_add_u32 s34, s24, s10
	s_addc_u32 s35, s25, 0
	s_lshl_b64 s[10:11], s[22:23], 10
	s_add_u32 s34, s34, s10
	s_addc_u32 s35, s35, s11
	s_waitcnt vmcnt(3)
	v_mov_b64_e32 v[0:1], v[56:57]
	v_mov_b64_e32 v[2:3], v[58:59]
	v_mov_b64_e32 v[34:35], v[64:65]
	v_mov_b64_e32 v[36:37], v[66:67]
	v_pk_mul_f32 v[38:39], v[2:3], v[2:3]
	v_pk_mul_f32 v[40:41], v[0:1], v[0:1]
	s_nop 0
	v_pk_mov_b32 v[42:43], v[40:41], v[38:39] op_sel:[1,0]
	v_mov_b32_e32 v41, v39
	v_pk_add_f32 v[38:39], v[42:43], v[40:41]
	s_nop 0
	v_add_f32_e32 v38, v38, v39
	ds_bpermute_b32 v39, v26, v38
	s_waitcnt lgkmcnt(0)
	v_add_f32_e32 v38, v38, v39
	ds_bpermute_b32 v39, v27, v38
	s_waitcnt lgkmcnt(0)
	v_add_f32_e32 v38, v38, v39
	ds_bpermute_b32 v39, v28, v38
	s_waitcnt lgkmcnt(0)
	v_add_f32_e32 v38, v38, v39
	ds_bpermute_b32 v39, v29, v38
	s_waitcnt lgkmcnt(0)
	v_add_f32_e32 v38, v38, v39
	ds_bpermute_b32 v39, v30, v38
	s_waitcnt lgkmcnt(0)
	v_add_f32_e32 v38, v38, v39
	ds_bpermute_b32 v39, v31, v38
	s_waitcnt lgkmcnt(0)
	v_add_f32_e32 v38, v38, v39
	v_fmamk_f32 v38, v38, 0x3b800000, v32
	v_mul_f32_e32 v39, 0x4f800000, v38
	v_cmp_gt_f32_e32 vcc, s28, v38
	s_nop 1
	v_cndmask_b32_e32 v38, v38, v39, vcc
	v_sqrt_f32_e32 v39, v38
	s_nop 0
	v_add_u32_e32 v40, -1, v39
	v_add_u32_e32 v41, 1, v39
	v_fma_f32 v42, -v40, v39, v38
	v_fma_f32 v43, -v41, v39, v38
	v_cmp_ge_f32_e64 s[10:11], 0, v42
	s_nop 1
	v_cndmask_b32_e64 v39, v39, v40, s[10:11]
	v_cmp_lt_f32_e64 s[10:11], 0, v43
	s_nop 1
	v_cndmask_b32_e64 v39, v39, v41, s[10:11]
	v_mul_f32_e32 v40, 0x37800000, v39
	v_cndmask_b32_e32 v39, v39, v40, vcc
	v_cmp_class_f32_e32 vcc, v38, v33
	s_nop 1
	v_cndmask_b32_e32 v40, v39, v38, vcc
	v_div_scale_f32 v41, s[10:11], v40, v40, 1.0
	v_rcp_f32_e32 v42, v41
	v_div_scale_f32 v43, vcc, 1.0, v40, 1.0
	v_lshl_add_u64 v[38:39], s[34:35], 0, v[24:25]
	v_fma_f32 v44, -v41, v42, 1.0
	v_fmac_f32_e32 v42, v44, v42
	v_mul_f32_e32 v44, v43, v42
	v_fma_f32 v45, -v41, v44, v43
	v_fmac_f32_e32 v44, v45, v42
	v_fma_f32 v41, -v41, v44, v43
	v_div_fmas_f32 v41, v41, v42, v44
	v_div_fixup_f32 v40, v41, v40, 1.0
	v_pk_mul_f32 v[0:1], v[0:1], v[40:41] op_sel_hi:[1,0]
	v_pk_mul_f32 v[2:3], v[2:3], v[40:41] op_sel_hi:[1,0]
	v_pk_mul_f32 v[0:1], v[34:35], v[0:1]
	v_pk_mul_f32 v[2:3], v[36:37], v[2:3]
	s_mov_b64 vcc, s[8:9]
	global_store_dwordx4 v[38:39], v[0:3], off
	s_cbranch_vccnz .LBB0_2256
	s_lshr_b32 s8, s12, 6
	s_mulk_i32 s8, 0x440
	s_and_b32 s9, s18, 63
	s_or_b32 s8, s8, s9
	s_add_i32 s12, s8, 0x8400
	s_mov_b64 s[20:21], s[12:13]
.LBB0_2256:
	s_lshl_b64 s[8:9], s[20:21], 9
	v_cvt_pk_bf16_f32 v0, v0, v1
	v_cvt_pk_bf16_f32 v1, v2, v3
	v_lshl_add_u64 v[2:3], v[10:11], 0, s[8:9]
	global_store_dwordx2 v[2:3], v[0:1], off
	s_and_saveexec_b64 s[8:9], s[6:7]
	s_cbranch_execz .LBB0_2253
	s_and_b32 s10, s18, 63
	s_and_b32 s12, s18, 0x1fff
	s_or_b32 s34, s10, 0x400
	s_and_b64 s[10:11], s[26:27], exec
	s_cselect_b32 s10, s12, s34
	v_lshl_add_u64 v[0:1], s[50:51], 0, v[18:19]
	s_lshl_b32 s12, s10, 8
	v_add_co_u32_e32 v0, vcc, 0xe000000, v0
	v_lshl_add_u64 v[2:3], v[12:13], 0, s[12:13]
	s_nop 0
	v_addc_co_u32_e32 v1, vcc, 0, v1, vcc
	global_load_dwordx2 v[34:35], v[2:3], off
	global_load_dword v36, v[0:1], off offset:2688
	global_load_dword v37, v[0:1], off offset:2560
	s_and_b64 s[10:11], s[26:27], exec
	s_cselect_b32 s10, s31, 0xc400000
	s_add_u32 s12, s24, s10
	s_addc_u32 s24, s25, 0
	s_lshl_b64 s[10:11], s[22:23], 8
	s_add_u32 s10, s12, s10
	s_addc_u32 s11, s24, s11
	v_lshl_add_u64 v[0:1], s[10:11], 0, v[4:5]
	s_lshl_b64 s[20:21], s[20:21], 7
	v_lshl_add_u64 v[2:3], v[14:15], 0, s[20:21]
	s_waitcnt vmcnt(0) lgkmcnt(0)
	v_mul_f32_e32 v38, v36, v35
	v_mul_f32_e32 v36, v36, v34
	v_fma_f32 v34, v37, v34, -v38
	v_fmac_f32_e32 v36, v37, v35
	global_store_dword v[0:1], v34, off
	global_store_dword v[0:1], v36, off offset:128
	v_bfe_u32 v0, v34, 16, 1
	v_bfe_u32 v1, v36, 16, 1
	v_add3_u32 v0, v34, v0, s33
	v_add3_u32 v1, v36, v1, s33
	global_store_short_d16_hi v[2:3], v0, off
	global_store_short_d16_hi v[2:3], v1, off offset:64
	s_branch .LBB0_2253
